# agent-scope (write-through) stores in the P5 projection epilogue so the full P5|P6 barrier has little left to flush
# speedup vs baseline: 1.0042x; 1.0042x over previous
; __device__ __forceinline__ unsigned pk2(float lo, float hi) { const f32x2c v = {lo, hi}; const bf16x2c b = __builtin_convertvector(v, bf16x2c); return __builtin_bit_cast(unsigned, b); }
;     __device__ __forceinline__ void operator()(const f32x4 (&acc)[2][2][4][2], const pg8::Unit& u, int wr, int wc, int fr, int fq) const {
;         const int row0 = u.pm * 256 + wr * 64 + fr; int colt = u.pn * 256; bf16_t* bp = PA; int ld = NPA;
;         if (colt >= NPA) { bp = PB; ld = NPB; colt -= NPA; }
;         const int col0 = colt + wc * 32 + 8 * fq;
; #pragma unroll
;         for (int ai = 0; ai < 2; ++ai)
; #pragma unroll
;             for (int m = 0; m < 4; ++m) {
;                 bf16_t* rowp = bp + (size_t)(row0 + ai * 128 + m * 16) * ld + col0;
; #pragma unroll
;                 for (int bj = 0; bj < 2; ++bj) {
;                     const f32x4 v0 = acc[ai][bj][m][0], v1 = acc[ai][bj][m][1];
;                     u32x4 w; w.x = pk2(v0[0], v0[1]); w.y = pk2(v0[2], v0[3]); w.z = pk2(v1[0], v1[1]); w.w = pk2(v1[2], v1[3]);
;                     *(u32x4*)(rowp + bj * 128) = w;
;                 }
;             }
;     }
.LBB0_376:
	v_lshl_add_u32 v154, s10, 8, v144
	s_lshl_b32 s10, s48, 8
	s_add_i32 s17, s10, 0xfffff900
	s_cmp_gt_i32 s48, 6
	v_readlane_b32 s26, v244, 29
	s_cselect_b32 s10, s17, s10
	v_readlane_b32 s27, v244, 30
	s_movk_i32 s21, 0x600
	s_cselect_b32 s17, s27, s97
	s_cselect_b32 s26, s26, s96
	v_add_u32_e32 v152, s10, v146
	s_cselect_b32 s21, s21, 0x700
	v_mov_b32_e32 v150, s26
	v_mov_b32_e32 v151, s17
	v_ashrrev_i32_e32 v153, 31, v152
	v_lshl_add_u64 v[150:151], v[152:153], 1, v[150:151]
	v_mad_i64_i32 v[152:153], s[26:27], s21, v154, 0
	v_cvt_pk_bf16_f32 v108, v108, v109
	v_cvt_pk_bf16_f32 v109, v110, v111
	v_cvt_pk_bf16_f32 v110, v104, v105
	v_or_b32_e32 v104, 16, v154
	v_lshl_add_u64 v[152:153], v[152:153], 1, v[150:151]
	v_cvt_pk_bf16_f32 v111, v106, v107
	v_mad_i64_i32 v[104:105], s[26:27], s21, v104, 0
	v_cvt_pk_bf16_f32 v92, v92, v93
	v_cvt_pk_bf16_f32 v93, v94, v95
	v_cvt_pk_bf16_f32 v94, v88, v89
	v_or_b32_e32 v88, 32, v154
	v_cvt_pk_bf16_f32 v124, v124, v125
	v_cvt_pk_bf16_f32 v125, v126, v127
	v_cvt_pk_bf16_f32 v126, v120, v121
	v_cvt_pk_bf16_f32 v127, v122, v123
	global_store_dwordx4 v[152:153], v[108:111], off offset:256 sc1
	v_cvt_pk_bf16_f32 v95, v90, v91
	v_mad_i64_i32 v[88:89], s[26:27], s21, v88, 0
	v_lshl_add_u64 v[108:109], v[104:105], 1, v[150:151]
	v_cvt_pk_bf16_f32 v76, v76, v77
	v_cvt_pk_bf16_f32 v77, v78, v79
	v_cvt_pk_bf16_f32 v78, v72, v73
	v_or_b32_e32 v72, 48, v154
	v_cvt_pk_bf16_f32 v68, v68, v69
	v_cvt_pk_bf16_f32 v69, v70, v71
	v_cvt_pk_bf16_f32 v70, v64, v65
	v_add_u32_e32 v64, 0x80, v154
	global_store_dwordx4 v[152:153], v[124:127], off sc1
	v_cvt_pk_bf16_f32 v104, v116, v117
	v_cvt_pk_bf16_f32 v105, v118, v119
	v_cvt_pk_bf16_f32 v106, v112, v113
	v_cvt_pk_bf16_f32 v107, v114, v115
	global_store_dwordx4 v[108:109], v[92:95], off offset:256 sc1
	v_cvt_pk_bf16_f32 v79, v74, v75
	v_mad_i64_i32 v[72:73], s[26:27], s21, v72, 0
	v_lshl_add_u64 v[92:93], v[88:89], 1, v[150:151]
	v_mad_i64_i32 v[64:65], s[26:27], s21, v64, 0
	v_cvt_pk_bf16_f32 v44, v44, v45
	v_cvt_pk_bf16_f32 v45, v46, v47
	v_cvt_pk_bf16_f32 v46, v40, v41
	v_add_u32_e32 v40, 0x90, v154
	global_store_dwordx4 v[108:109], v[104:107], off sc1
	v_cvt_pk_bf16_f32 v88, v100, v101
	v_cvt_pk_bf16_f32 v89, v102, v103
	v_cvt_pk_bf16_f32 v90, v96, v97
	v_cvt_pk_bf16_f32 v91, v98, v99
	global_store_dwordx4 v[92:93], v[76:79], off offset:256 sc1
	v_cvt_pk_bf16_f32 v74, v80, v81
	v_cvt_pk_bf16_f32 v75, v82, v83
	v_lshl_add_u64 v[76:77], v[72:73], 1, v[150:151]
	v_cvt_pk_bf16_f32 v72, v84, v85
	v_cvt_pk_bf16_f32 v73, v86, v87
	v_cvt_pk_bf16_f32 v71, v66, v67
	v_lshl_add_u64 v[64:65], v[64:65], 1, v[150:151]
	v_cvt_pk_bf16_f32 v47, v42, v43
	v_mad_i64_i32 v[40:41], s[26:27], s21, v40, 0
	v_cvt_pk_bf16_f32 v28, v28, v29
	v_cvt_pk_bf16_f32 v29, v30, v31
	v_cvt_pk_bf16_f32 v30, v24, v25
	v_add_u32_e32 v24, 0xa0, v154
	global_store_dwordx4 v[92:93], v[88:91], off sc1
	global_store_dwordx4 v[76:77], v[72:75], off sc1
	global_store_dwordx4 v[76:77], v[68:71], off offset:256 sc1
	v_cvt_pk_bf16_f32 v60, v60, v61
	v_cvt_pk_bf16_f32 v61, v62, v63
	v_cvt_pk_bf16_f32 v62, v56, v57
	v_cvt_pk_bf16_f32 v63, v58, v59
	global_store_dwordx4 v[64:65], v[44:47], off offset:256 sc1
	v_cvt_pk_bf16_f32 v31, v26, v27
	v_mad_i64_i32 v[24:25], s[26:27], s21, v24, 0
	v_lshl_add_u64 v[44:45], v[40:41], 1, v[150:151]
	v_cvt_pk_bf16_f32 v12, v12, v13
	v_cvt_pk_bf16_f32 v13, v14, v15
	v_cvt_pk_bf16_f32 v14, v8, v9
	v_add_u32_e32 v8, 0xb0, v154
	global_store_dwordx4 v[64:65], v[60:63], off sc1
	v_cvt_pk_bf16_f32 v40, v52, v53
	v_cvt_pk_bf16_f32 v41, v54, v55
	v_cvt_pk_bf16_f32 v42, v48, v49
	v_cvt_pk_bf16_f32 v43, v50, v51
	global_store_dwordx4 v[44:45], v[28:31], off offset:256 sc1
	v_cvt_pk_bf16_f32 v15, v10, v11
	v_mad_i64_i32 v[8:9], s[26:27], s21, v8, 0
	v_lshl_add_u64 v[28:29], v[24:25], 1, v[150:151]
	global_store_dwordx4 v[44:45], v[40:43], off sc1
	v_cvt_pk_bf16_f32 v24, v36, v37
	v_cvt_pk_bf16_f32 v25, v38, v39
	v_cvt_pk_bf16_f32 v26, v32, v33
	v_cvt_pk_bf16_f32 v27, v34, v35
	global_store_dwordx4 v[28:29], v[12:15], off offset:256 sc1
	v_cvt_pk_bf16_f32 v10, v16, v17
	v_cvt_pk_bf16_f32 v11, v18, v19
	v_lshl_add_u64 v[12:13], v[8:9], 1, v[150:151]
	v_cvt_pk_bf16_f32 v8, v20, v21
	v_cvt_pk_bf16_f32 v9, v22, v23
	v_cvt_pk_bf16_f32 v4, v4, v5
	v_cvt_pk_bf16_f32 v5, v6, v7
	v_cvt_pk_bf16_f32 v6, v0, v1
	v_cvt_pk_bf16_f32 v7, v2, v3
	s_andn2_b64 vcc, exec, s[4:5]
	s_mov_b64 s[4:5], -1
	global_store_dwordx4 v[28:29], v[24:27], off sc1
	global_store_dwordx4 v[12:13], v[8:11], off sc1
	global_store_dwordx4 v[12:13], v[4:7], off offset:256 sc1
	s_cbranch_vccnz .LBB0_369
	s_andn2_b64 vcc, exec, s[0:1]
	s_cbranch_vccnz .LBB0_368
	s_barrier
	s_branch .LBB0_368
